# second half of softmax-1 (exp/cvt/swap of the last 16 keys) moved under the first four PV1 MFMAs; PV1 reordered k-step-0 first
# speedup vs baseline: 1.0380x; 1.0023x over previous
; #define VWAIT(N, f) asm volatile("s_waitcnt lgkmcnt(" #N ")" : "+v"(f.l0), "+v"(f.h0), "+v"(f.l1), "+v"(f.h1) :: "memory")
; template <int H, int D0> __device__ __forceinline__ VFrag pv_rd(int vb) {
;   VFrag f; f.l0 = tr_read<v_rd_off(D0, 2 * H, 0)>(vb); f.h0 = tr_read<v_rd_off(D0, 2 * H, 1)>(vb); f.l1 = tr_read<v_rd_off(D0, 2 * H + 1, 0)>(vb); f.h1 = tr_read<v_rd_off(D0, 2 * H + 1, 1)>(vb); return f;
; }
; __device__ __forceinline__ void pv_mma(f32x16& od, VFrag& f, bf16x8 paL, bf16x8 paH) {
;     ...
;   od = __builtin_amdgcn_mfma_f32_32x32x16_bf16(paL, PK(f.l0, f.h0), od, 0, 0, 0);
;   od = __builtin_amdgcn_mfma_f32_32x32x16_bf16(paH, PK(f.l1, f.h1), od, 0, 0, 0);
;     ...
; }
; template <int H> __device__ __forceinline__ void pv_half(f32x16* o, int vb, bf16x8 paL, bf16x8 paH) {
;   VFrag fa = pv_rd<H, 0>(vb), fb = pv_rd<H, 1>(vb);
;   VWAIT(4, fa); pv_mma(o[0], fa, paL, paH);
;   fa = pv_rd<H, 2>(vb);
;   VWAIT(4, fb); pv_mma(o[1], fb, paL, paH);
;   fb = pv_rd<H, 3>(vb);
;   VWAIT(4, fa); pv_mma(o[2], fa, paL, paH);
;   VWAIT(0, fb); pv_mma(o[3], fb, paL, paH);
; }
.LBB0_518:
	v_fma_f32 v202, v197, v0, v198
	v_fma_f32 v0, v202, v200, v201
	v_fma_f32 v202, v0, v249, v91
	ds_read_b64_tr_b16 v[204:205], v181 offset:0x2000
	ds_read_b64_tr_b16 v[206:207], v181 offset:0x2800
	ds_read_b64_tr_b16 v[82:83], v181 offset:0x2200
	ds_read_b64_tr_b16 v[84:85], v181 offset:0x2a00
	ds_read_b64_tr_b16 v[212:213], v181 offset:0x2400
	ds_read_b64_tr_b16 v[214:215], v181 offset:0x2c00
	ds_read_b64_tr_b16 v[216:217], v181 offset:0x2600
	ds_read_b64_tr_b16 v[218:219], v181 offset:0x2e00
	ds_read_b64_tr_b16 v[208:209], v181 offset:0x3000
	ds_read_b64_tr_b16 v[210:211], v181 offset:0x3800
	ds_read_b64_tr_b16 v[86:87], v181 offset:0x3200
	ds_read_b64_tr_b16 v[88:89], v181 offset:0x3a00
	v_exp_f32_e32 v74, v74
	v_exp_f32_e32 v75, v75
	s_add_i32 s87, s87, 2
	s_and_b64 vcc, exec, s[62:63]
	s_waitcnt lgkmcnt(10)
	v_mfma_f32_32x32x16_bf16 v[50:65], v[66:69], v[204:207], v[50:65]
	ds_read_b64_tr_b16 v[204:205], v181 offset:0x3400
	ds_read_b64_tr_b16 v[206:207], v181 offset:0x3c00
	v_exp_f32_e32 v76, v76
	v_exp_f32_e32 v77, v77
	v_add_f32_e32 v163, v74, v163
	v_add_f32_e32 v163, v75, v163
	s_waitcnt lgkmcnt(10)
	v_mfma_f32_32x32x16_bf16 v[34:49], v[66:69], v[82:85], v[34:49]
	ds_read_b64_tr_b16 v[82:83], v181 offset:0x3600
	ds_read_b64_tr_b16 v[84:85], v181 offset:0x3e00
	v_exp_f32_e32 v78, v78
	v_exp_f32_e32 v79, v79
	v_add_f32_e32 v163, v76, v163
	v_add_f32_e32 v163, v77, v163
	v_cvt_pk_bf16_f32 v70, v74, v75
	v_cvt_pk_bf16_f32 v71, v76, v77
	s_waitcnt lgkmcnt(10)
	v_mfma_f32_32x32x16_bf16 v[18:33], v[66:69], v[212:215], v[18:33]
	v_exp_f32_e32 v80, v80
	v_exp_f32_e32 v81, v81
	v_add_f32_e32 v163, v78, v163
	v_add_f32_e32 v163, v79, v163
	s_waitcnt lgkmcnt(8)
	v_mfma_f32_32x32x16_bf16 v[2:17], v[66:69], v[216:219], v[2:17]
	v_cvt_pk_bf16_f32 v72, v78, v79
	v_add_f32_e32 v163, v80, v163
	v_add_f32_e32 v163, v81, v163
	v_cvt_pk_bf16_f32 v73, v80, v81
	s_nop 1
	v_permlane32_swap_b32_e32 v70, v72
	v_permlane32_swap_b32_e32 v71, v73
	s_nop 1
	s_waitcnt vmcnt(0) lgkmcnt(0)
	v_mfma_f32_32x32x16_bf16 v[50:65], v[70:73], v[208:211], v[50:65]
	s_barrier
	v_mfma_f32_32x32x16_bf16 v[34:49], v[70:73], v[86:89], v[34:49]
	v_mfma_f32_32x32x16_bf16 v[18:33], v[70:73], v[204:207], v[18:33]
	v_mfma_f32_32x32x16_bf16 v[2:17], v[70:73], v[82:85], v[2:17]
	v_fma_f32 v197, v202, v93, v163
	s_cbranch_vccnz .LBB0_542

; __device__ __forceinline__ void sm_half(f32x16& p, float& m_reg, float& l_reg, float& alpha, bf16x8& paL, bf16x8& paH) {
;   float a = fmaxf(fmaxf(p[0], p[1]), p[2]), b = fmaxf(fmaxf(p[3], p[4]), p[5]);
;   a = fmaxf(fmaxf(a, p[6]), p[7]); b = fmaxf(fmaxf(b, p[8]), p[9]); a = fmaxf(fmaxf(a, p[10]), p[11]); b = fmaxf(fmaxf(b, p[12]), p[13]); a = fmaxf(fmaxf(a, p[14]), p[15]);
;   float pmax = fmaxf(a, b);
;   { auto rr = __builtin_amdgcn_permlane32_swap(__float_as_uint(pmax), __float_as_uint(pmax), false, false);
;     pmax = fmaxf(__uint_as_float(rr[0]), __uint_as_float(rr[1])); }
;   const bool keep = __all(pmax - m_reg <= THRL);
;   const float mn = keep ? m_reg : fmaxf(m_reg, pmax);
;   alpha = __builtin_amdgcn_exp2f(m_reg - mn); m_reg = mn;
; #pragma unroll
;   for (int r = 0; r < 16; ++r) p[r] = __builtin_amdgcn_exp2f(p[r] - mn);
;   float ps = 0;
; #pragma unroll
;   for (int r = 0; r < 16; ++r) ps += p[r];
;   { auto rr = __builtin_amdgcn_permlane32_swap(__float_as_uint(ps), __float_as_uint(ps), false, false);
;     ps = __uint_as_float(rr[0]) + __uint_as_float(rr[1]); }
;   l_reg = l_reg * alpha + ps;
;     ...
;   PK4(p, 0, paL); PK4(p, 8, paH);
;     ...
; }
; template <int H> __device__ __forceinline__ void qkt_half(f32x16& p, const char* Kn, const char* Kr, const bf16x8* qr, int r32, int hi) {
;   p = f32x16{};
; #pragma unroll
;   for (int d0 = 0; d0 < 8; ++d0) { const int cb = (d0 * 16 + hi * 8) * 2;
;     const bf16x8 f = *reinterpret_cast<const bf16x8*>(Kn + KSWZ(32 * H + r32, cb)); p = __builtin_amdgcn_mfma_f32_32x32x16_bf16(f, qr[d0], p, 0, 0, 0); }
; #pragma unroll
;   for (int d0 = 0; d0 < 4; ++d0) { const int cb = (d0 * 16 + hi * 8) * 2;
;     const bf16x8 f = *reinterpret_cast<const bf16x8*>(Kr + KRSWZ(32 * H + r32, cb)); p = __builtin_amdgcn_mfma_f32_32x32x16_bf16(f, qr[8 + d0], p, 0, 0, 0); }
; }
; template <int H, int D0> __device__ __forceinline__ VFrag pv_rd(int vb) {
;   VFrag f; f.l0 = tr_read<v_rd_off(D0, 2 * H, 0)>(vb); f.h0 = tr_read<v_rd_off(D0, 2 * H, 1)>(vb); f.l1 = tr_read<v_rd_off(D0, 2 * H + 1, 0)>(vb); f.h1 = tr_read<v_rd_off(D0, 2 * H + 1, 1)>(vb); return f;
; }
; __device__ __forceinline__ void pv_mma(f32x16& od, VFrag& f, bf16x8 paL, bf16x8 paH) {
;     ...
;   od = __builtin_amdgcn_mfma_f32_32x32x16_bf16(paL, PK(f.l0, f.h0), od, 0, 0, 0);
;   od = __builtin_amdgcn_mfma_f32_32x32x16_bf16(paH, PK(f.l1, f.h1), od, 0, 0, 0);
;     ...
; }
.Lcont_01:
	v_exp_f32_e32 v66, v66
	v_exp_f32_e32 v67, v67
	v_exp_f32_e32 v68, v68
	v_exp_f32_e32 v69, v69
	v_mfma_f32_32x32x16_bf16 v[2:17], v[82:85], v[214:217], v[2:17]
	v_exp_f32_e32 v70, v70
	v_exp_f32_e32 v71, v71
	v_add_f32_e32 v201, v67, v66
	v_exp_f32_e32 v72, v72
	v_add_f32_e32 v201, v68, v201
	v_exp_f32_e32 v73, v73
	v_add_f32_e32 v201, v69, v201
	v_add_f32_e32 v201, v70, v201
	v_add_f32_e32 v201, v71, v201
	v_add_f32_e32 v201, v72, v201
	v_add_f32_e32 v201, v73, v201
	v_mfma_f32_32x32x16_bf16 v[34:49], v[86:89], v[206:209], v[34:49]
	v_mfma_f32_32x32x16_bf16 v[18:33], v[86:89], v[210:213], v[18:33]
	v_cvt_pk_bf16_f32 v66, v66, v67
	v_cvt_pk_bf16_f32 v67, v68, v69
	v_mfma_f32_32x32x16_bf16 v[2:17], v[86:89], v[94:97], v[2:17]
	v_cvt_pk_bf16_f32 v68, v70, v71
	v_cvt_pk_bf16_f32 v69, v72, v73
	s_nop 0
	v_permlane32_swap_b32_e32 v66, v68
	v_permlane32_swap_b32_e32 v67, v69
	s_cbranch_scc1 .LBB0_531
	s_and_saveexec_b64 s[62:63], s[0:1]
	ds_write_b32 v196, v200 offset:128
	s_or_b64 exec, exec, s[62:63]
	s_waitcnt lgkmcnt(0)
	v_add_u32_e32 v86, s80, v176
	ds_read_b128 v[90:93], v86 offset:224
	ds_read_b128 v[94:97], v86 offset:192
	ds_read_b128 v[82:85], v86 offset:160
	ds_read_b128 v[86:89], v86 offset:128
	s_waitcnt lgkmcnt(0)
	v_pk_mul_f32 v[62:63], v[62:63], v[90:91]
	v_pk_mul_f32 v[58:59], v[58:59], v[94:95]
	v_pk_mul_f32 v[54:55], v[54:55], v[82:83]
	v_pk_mul_f32 v[64:65], v[64:65], v[92:93]
	v_pk_mul_f32 v[60:61], v[60:61], v[96:97]
	v_pk_mul_f32 v[56:57], v[56:57], v[84:85]
	v_pk_mul_f32 v[52:53], v[52:53], v[88:89]
	v_pk_mul_f32 v[50:51], v[50:51], v[86:87]
	v_pk_mul_f32 v[46:47], v[46:47], v[90:91]
	v_pk_mul_f32 v[42:43], v[42:43], v[94:95]
	v_pk_mul_f32 v[38:39], v[38:39], v[82:83]
	v_pk_mul_f32 v[48:49], v[48:49], v[92:93]
	v_pk_mul_f32 v[44:45], v[44:45], v[96:97]
	v_pk_mul_f32 v[40:41], v[40:41], v[84:85]
	v_pk_mul_f32 v[36:37], v[36:37], v[88:89]
	v_pk_mul_f32 v[34:35], v[34:35], v[86:87]
	v_pk_mul_f32 v[30:31], v[30:31], v[90:91]
	v_pk_mul_f32 v[26:27], v[26:27], v[94:95]
	v_pk_mul_f32 v[22:23], v[22:23], v[82:83]
	v_pk_mul_f32 v[32:33], v[32:33], v[92:93]
	v_pk_mul_f32 v[28:29], v[28:29], v[96:97]
	v_pk_mul_f32 v[24:25], v[24:25], v[84:85]
	v_pk_mul_f32 v[20:21], v[20:21], v[88:89]
	v_pk_mul_f32 v[18:19], v[18:19], v[86:87]
	v_pk_mul_f32 v[14:15], v[14:15], v[90:91]
	v_pk_mul_f32 v[10:11], v[10:11], v[94:95]
	v_pk_mul_f32 v[6:7], v[6:7], v[82:83]
	v_pk_mul_f32 v[16:17], v[16:17], v[92:93]
	v_pk_mul_f32 v[12:13], v[12:13], v[96:97]
	v_pk_mul_f32 v[8:9], v[8:9], v[84:85]
	v_pk_mul_f32 v[4:5], v[4:5], v[88:89]
	v_pk_mul_f32 v[2:3], v[2:3], v[86:87]
.LBB0_531:
	ds_read_b64_tr_b16 v[90:91], v175 offset:0x2000
	ds_read_b64_tr_b16 v[92:93], v175 offset:0x2800
	ds_read_b64_tr_b16 v[82:83], v175 offset:0x2200
	ds_read_b64_tr_b16 v[84:85], v175 offset:0x2a00
	ds_read_b64_tr_b16 v[202:203], v175 offset:0x2400
	ds_read_b64_tr_b16 v[204:205], v175 offset:0x2c00
	ds_read_b64_tr_b16 v[206:207], v175 offset:0x2600
	ds_read_b64_tr_b16 v[208:209], v175 offset:0x2e00
	ds_read_b64_tr_b16 v[94:95], v175 offset:0x3000
	ds_read_b64_tr_b16 v[96:97], v175 offset:0x3800
	ds_read_b64_tr_b16 v[86:87], v175 offset:0x3200
	ds_read_b64_tr_b16 v[88:89], v175 offset:0x3a00
	v_exp_f32_e32 v74, v74
	v_exp_f32_e32 v75, v75
	s_cmp_lt_u32 s87, s79
	s_cselect_b64 s[64:65], -1, 0
	s_cmp_ge_u32 s87, s79
	s_cselect_b64 s[62:63], -1, 0
	s_and_b64 vcc, exec, s[62:63]
	s_waitcnt lgkmcnt(10)
	v_mfma_f32_32x32x16_bf16 v[50:65], v[66:69], v[90:93], v[50:65]
	ds_read_b64_tr_b16 v[90:91], v175 offset:0x3400
	ds_read_b64_tr_b16 v[92:93], v175 offset:0x3c00
	v_exp_f32_e32 v76, v76
	v_exp_f32_e32 v77, v77
	v_add_f32_e32 v201, v74, v201
	v_add_f32_e32 v201, v75, v201
	s_waitcnt lgkmcnt(10)
	v_mfma_f32_32x32x16_bf16 v[34:49], v[66:69], v[82:85], v[34:49]
	ds_read_b64_tr_b16 v[82:83], v175 offset:0x3600
	ds_read_b64_tr_b16 v[84:85], v175 offset:0x3e00
	v_exp_f32_e32 v78, v78
	v_exp_f32_e32 v79, v79
	v_add_f32_e32 v201, v76, v201
	v_add_f32_e32 v201, v77, v201
	v_cvt_pk_bf16_f32 v70, v74, v75
	v_cvt_pk_bf16_f32 v71, v76, v77
	s_waitcnt lgkmcnt(10)
	v_mfma_f32_32x32x16_bf16 v[18:33], v[66:69], v[202:205], v[18:33]
	v_exp_f32_e32 v80, v80
	v_exp_f32_e32 v81, v81
	v_add_f32_e32 v201, v78, v201
	v_add_f32_e32 v201, v79, v201
	s_waitcnt lgkmcnt(8)
	v_mfma_f32_32x32x16_bf16 v[2:17], v[66:69], v[206:209], v[2:17]
	v_cvt_pk_bf16_f32 v72, v78, v79
	v_add_f32_e32 v201, v80, v201
	v_add_f32_e32 v201, v81, v201
	v_cvt_pk_bf16_f32 v73, v80, v81
	s_nop 1
	v_permlane32_swap_b32_e32 v70, v72
	v_permlane32_swap_b32_e32 v71, v73
	s_nop 1
	s_waitcnt vmcnt(0) lgkmcnt(0)
	v_mfma_f32_32x32x16_bf16 v[50:65], v[70:73], v[94:97], v[50:65]
	s_barrier
	v_mfma_f32_32x32x16_bf16 v[34:49], v[70:73], v[86:89], v[34:49]
	v_mfma_f32_32x32x16_bf16 v[18:33], v[70:73], v[90:93], v[18:33]
	v_mfma_f32_32x32x16_bf16 v[2:17], v[70:73], v[82:85], v[2:17]
	s_cbranch_vccnz .LBB0_533
	s_mov_b32 m0, s82
	s_nop 0
	global_load_lds_dwordx4 v152, s[18:19]
	s_mov_b32 m0, s83
	s_nop 0
	global_load_lds_dwordx4 v153, s[18:19]
	s_add_u32 s18, s18, 0x18000
	s_addc_u32 s19, s19, 0

; __device__ __forceinline__ void sm_half(f32x16& p, float& m_reg, float& l_reg, float& alpha, bf16x8& paL, bf16x8& paH) {
;     ...
;   for (int r = 0; r < 16; ++r) p[r] = __builtin_amdgcn_exp2f(p[r] - mn);
;   float ps = 0;
; #pragma unroll
;   for (int r = 0; r < 16; ++r) ps += p[r];
;   { auto rr = __builtin_amdgcn_permlane32_swap(__float_as_uint(ps), __float_as_uint(ps), false, false);
;     ps = __uint_as_float(rr[0]) + __uint_as_float(rr[1]); }
;   l_reg = l_reg * alpha + ps;
;     ...
;   PK4(p, 0, paL); PK4(p, 8, paH);
.Lcont_11:
	s_waitcnt lgkmcnt(0)
	v_mfma_f32_32x32x16_bf16 v[50:65], v[86:89], v[164:167], v[50:65]
	v_exp_f32_e32 v66, v66
	v_exp_f32_e32 v67, v67
	v_mfma_f32_32x32x16_bf16 v[34:49], v[82:85], v[168:171], v[34:49]
	v_exp_f32_e32 v68, v68
	v_exp_f32_e32 v69, v69
	v_exp_f32_e32 v70, v70
	v_exp_f32_e32 v71, v71
	v_mfma_f32_32x32x16_bf16 v[2:17], v[82:85], v[212:215], v[2:17]
	v_add_f32_e32 v163, v67, v66
	v_exp_f32_e32 v72, v72
	v_add_f32_e32 v163, v68, v163
	v_exp_f32_e32 v73, v73
	v_add_f32_e32 v163, v69, v163
	v_add_f32_e32 v163, v70, v163
	v_add_f32_e32 v163, v71, v163
	v_add_f32_e32 v163, v72, v163
	v_add_f32_e32 v163, v73, v163
	v_mfma_f32_32x32x16_bf16 v[34:49], v[86:89], v[204:207], v[34:49]
	v_mfma_f32_32x32x16_bf16 v[18:33], v[86:89], v[208:211], v[18:33]
	v_cvt_pk_bf16_f32 v66, v66, v67
	v_cvt_pk_bf16_f32 v67, v68, v69
	v_cvt_pk_bf16_f32 v68, v70, v71
	v_cvt_pk_bf16_f32 v69, v72, v73
	v_mfma_f32_32x32x16_bf16 v[2:17], v[86:89], v[216:219], v[2:17]
	s_nop 0
	v_permlane32_swap_b32_e32 v66, v68
	v_permlane32_swap_b32_e32 v67, v69
	s_cbranch_scc1 .LBB0_518
	s_and_saveexec_b64 s[64:65], s[0:1]
	s_cbranch_execz .LBB0_517
	ds_write_b32 v196, v93 offset:128
	s_branch .LBB0_517
